# P5 epilogue: 8 serialized sab row loads issued together; mid() K-half rescale loads all 8 row pairs up front
# speedup vs baseline: 1.0130x; 1.0130x over previous
;     __device__ __forceinline__ void operator()(const f32x4 (&acc)[2][2][4][2], const Unit& u, int wr, int wc, int fr, int fq) const {
;     ...
;         GAS const float* rb = (GAS const float*)((u.pm < MP / BM) ? r0 : r1);
;         GAS float* Cg = (GAS float*)C; GAS bf16_t* Hg = (GAS bf16_t*)HG; GAS const float* sabg = (GAS const float*)sab; GAS float* ssqg = (GAS float*)ssq;
;         f32x4 gc[2][2]; float rsb[8];
;         if (HG) {
; #pragma unroll
;             for (int bj = 0; bj < 2; ++bj)
; #pragma unroll
;                 for (int n = 0; n < 2; ++n) gc[bj][n] = *(GAS const f32x4*)((GAS const float*)gcol + col0 + bj * HALF + n * 4); }
; #pragma unroll
;         for (int g = 0; g < 8; ++g) rsb[g] = sab ? sabg[2 * (size_t)(row0 + (g >> 2) * HALF + (g & 3) * 16) + 1] : 0.f;
;         f32x4 nx[2][2];
;         { const size_t off = (size_t)row0 * D + col0;
; #pragma unroll
;           for (int bj = 0; bj < 2; ++bj)
; #pragma unroll
;             for (int n = 0; n < 2; ++n) nx[bj][n] = *(GAS const f32x4*)(rb + off + bj * HALF + n * 4); }
; #pragma unroll
;         for (int g = 0; g < 8; ++g) { const int ai = g >> 2, m = g & 3;
;             const int row = row0 + ai * HALF + m * 16; const size_t off = (size_t)row * D + col0;
;             f32x4 cur[2][2];
; #pragma unroll
;             for (int bj = 0; bj < 2; ++bj)
; #pragma unroll
;                 for (int n = 0; n < 2; ++n) cur[bj][n] = nx[bj][n];
;             if (g < 7) { const size_t offn = (size_t)(row0 + ((g + 1) >> 2) * HALF + ((g + 1) & 3) * 16) * D + col0;
; #pragma unroll
;                 for (int bj = 0; bj < 2; ++bj)
; #pragma unroll
;                     for (int n = 0; n < 2; ++n) nx[bj][n] = *(GAS const f32x4*)(rb + offn + bj * HALF + n * 4); }
;             const float rs = sab ? rsqrtf(rsb[g] * (1.f / GW) + EPS) : 1.0f;
;             f32x4 v[2][2]; float ss = 0.f;
; #pragma unroll
;             for (int bj = 0; bj < 2; ++bj)
; #pragma unroll
;                 for (int n = 0; n < 2; ++n) { v[bj][n] = cur[bj][n] + acc[ai][bj][m][n] * rs; *(GAS f32x4*)(Cg + off + bj * HALF + n * 4) = v[bj][n];
;                     ss += (v[bj][n][0] * v[bj][n][0] + v[bj][n][1] * v[bj][n][1]) + (v[bj][n][2] * v[bj][n][2] + v[bj][n][3] * v[bj][n][3]); }
;             if (HG) {
; #pragma unroll
;                 for (int bj = 0; bj < 2; ++bj) { const f32x4 a0 = v[bj][0] * gc[bj][0], a1 = v[bj][1] * gc[bj][1];
.LBB0_1341:
	v_ashrrev_i32_e32 v3, 31, v2
	v_lshl_add_u64 v[148:149], v[2:3], 3, s[48:49]
	global_load_dword v152, v[148:149], off offset:4
	global_load_dword v218, v[148:149], off offset:132
	global_load_dword v239, v[148:149], off offset:260
	global_load_dword v238, v[148:149], off offset:388
	global_load_dword v237, v[148:149], off offset:1028
	global_load_dword v236, v[148:149], off offset:1156
	global_load_dword v235, v[148:149], off offset:1284
	global_load_dword v0, v[148:149], off offset:1412
.LBB0_1350:
	s_cmp_lt_i32 s88, 64
	v_ashrrev_i32_e32 v3, 31, v2
	s_cselect_b32 s3, s15, s17
	s_cselect_b32 s2, s14, s16
	v_ashrrev_i32_e32 v211, 31, v210
	v_lshlrev_b64 v[148:149], 13, v[2:3]
	v_lshl_add_u64 v[148:149], s[2:3], 0, v[148:149]
	v_lshlrev_b64 v[150:151], 2, v[210:211]
	v_or_b32_e32 v214, 16, v2
	v_lshl_add_u64 v[148:149], v[148:149], 0, v[150:151]
	v_ashrrev_i32_e32 v215, 31, v214
	global_load_dwordx4 v[164:167], v[148:149], off
	global_load_dwordx4 v[168:171], v[148:149], off offset:16
	global_load_dwordx4 v[240:243], v[148:149], off offset:528
	global_load_dwordx4 v[244:247], v[148:149], off offset:512
	v_lshl_add_u64 v[212:213], s[2:3], 0, v[150:151]
	v_lshlrev_b64 v[148:149], 13, v[214:215]
	v_lshl_add_u64 v[154:155], v[212:213], 0, v[148:149]
	global_load_dwordx4 v[160:163], v[154:155], off offset:16
	global_load_dwordx4 v[172:175], v[154:155], off
	global_load_dwordx4 v[148:151], v[154:155], off offset:528
	global_load_dwordx4 v[156:159], v[154:155], off offset:512
	s_waitcnt vmcnt(8)
	v_fmamk_f32 v152, v152, 0x3a800000, v223
	v_fmamk_f32 v218, v218, 0x3a800000, v223
	v_fmamk_f32 v239, v239, 0x3a800000, v223
	v_fmamk_f32 v238, v238, 0x3a800000, v223
	v_fmamk_f32 v237, v237, 0x3a800000, v223
	v_fmamk_f32 v236, v236, 0x3a800000, v223
	v_fmamk_f32 v235, v235, 0x3a800000, v223
	v_fmamk_f32 v0, v0, 0x3a800000, v223
	v_mul_f32_e32 v153, 0x4b800000, v152
	v_cmp_gt_f32_e64 s[46:47], s29, v152
	v_lshlrev_b64 v[154:155], 11, v[2:3]
	v_lshl_add_u64 v[180:181], v[154:155], 0, v[210:211]
	v_cndmask_b32_e64 v152, v152, v153, s[46:47]
	v_rsq_f32_e32 v152, v152
	s_and_b64 vcc, exec, s[44:45]
	v_lshl_add_u64 v[182:183], v[180:181], 2, s[8:9]
	v_mul_f32_e32 v153, 0x45800000, v152
	v_cndmask_b32_e64 v152, v152, v153, s[46:47]
	v_cndmask_b32_e64 v152, v152, 1.0, s[56:57]
	s_waitcnt vmcnt(0)
	v_pk_fma_f32 v[178:179], v[130:131], v[152:153], v[166:167] op_sel_hi:[1,0,1]
	v_pk_fma_f32 v[176:177], v[128:129], v[152:153], v[164:165] op_sel_hi:[1,0,1]
	v_pk_fma_f32 v[170:171], v[126:127], v[152:153], v[170:171] op_sel_hi:[1,0,1]
	v_pk_fma_f32 v[168:169], v[124:125], v[152:153], v[168:169] op_sel_hi:[1,0,1]
	v_pk_fma_f32 v[166:167], v[98:99], v[152:153], v[246:247] op_sel_hi:[1,0,1]
	v_pk_fma_f32 v[164:165], v[96:97], v[152:153], v[244:245] op_sel_hi:[1,0,1]
	v_pk_fma_f32 v[154:155], v[94:95], v[152:153], v[242:243] op_sel_hi:[1,0,1]
	v_pk_fma_f32 v[152:153], v[92:93], v[152:153], v[240:241] op_sel_hi:[1,0,1]
	global_store_dwordx4 v[182:183], v[176:179], off
	global_store_dwordx4 v[182:183], v[168:171], off offset:16
	global_store_dwordx4 v[182:183], v[164:167], off offset:512
	global_store_dwordx4 v[182:183], v[152:155], off offset:528
	s_cbranch_vccnz .LBB0_1354
	v_mul_f32_e32 v182, v177, v177
	v_mul_f32_e32 v183, v179, v179
	v_fmac_f32_e32 v182, v176, v176
	v_fmac_f32_e32 v183, v178, v178
	v_add_f32_e32 v182, v182, v183
	v_mul_f32_e32 v183, v169, v169
	v_mul_f32_e32 v216, v171, v171
	v_fmac_f32_e32 v183, v168, v168
	v_fmac_f32_e32 v216, v170, v170
	v_add_f32_e32 v183, v183, v216
	v_add_f32_e32 v182, v182, v183
	v_mul_f32_e32 v183, v165, v165
	v_mul_f32_e32 v216, v167, v167
	v_fmac_f32_e32 v183, v164, v164
	v_fmac_f32_e32 v216, v166, v166
	v_add_f32_e32 v183, v183, v216
	v_add_f32_e32 v182, v182, v183
	v_mul_f32_e32 v183, v153, v153
	v_mul_f32_e32 v216, v155, v155
	v_fmac_f32_e32 v183, v152, v152
	v_fmac_f32_e32 v216, v154, v154
	v_add_f32_e32 v183, v183, v216
	v_add_f32_e32 v216, v182, v183
	v_lshl_add_u64 v[180:181], v[180:181], 1, s[6:7]
	v_pk_mul_f32 v[178:179], v[146:147], v[178:179]
	v_pk_mul_f32 v[176:177], v[144:145], v[176:177]
	v_pk_mul_f32 v[182:183], v[142:143], v[170:171]
	v_pk_mul_f32 v[170:171], v[140:141], v[168:169]
	v_cvt_pk_bf16_f32 v168, v176, v177
	v_cvt_pk_bf16_f32 v169, v178, v179
	v_pk_mul_f32 v[166:167], v[138:139], v[166:167]
	v_cvt_pk_bf16_f32 v170, v170, v171
	v_cvt_pk_bf16_f32 v171, v182, v183
	global_store_dwordx4 v[180:181], v[168:171], off
	v_pk_mul_f32 v[164:165], v[136:137], v[164:165]
	v_pk_mul_f32 v[154:155], v[134:135], v[154:155]
	v_and_b32_e32 v169, 64, v221
	v_xor_b32_e32 v168, 16, v221
	v_add_u32_e32 v170, 64, v169
	v_cmp_lt_i32_e32 vcc, v168, v170
	v_cvt_pk_bf16_f32 v164, v164, v165
	v_cvt_pk_bf16_f32 v165, v166, v167
	s_nop 1
	v_cndmask_b32_e32 v168, v221, v168, vcc
	v_lshlrev_b32_e32 v168, 2, v168
	ds_bpermute_b32 v171, v168, v216
	v_pk_mul_f32 v[168:169], v[132:133], v[152:153]
	v_xor_b32_e32 v153, 32, v221
	v_cmp_lt_i32_e32 vcc, v153, v170
	v_cvt_pk_bf16_f32 v166, v168, v169
	s_waitcnt lgkmcnt(0)
	v_add_f32_e32 v152, v216, v171
	v_cvt_pk_bf16_f32 v167, v154, v155
	global_store_dwordx4 v[180:181], v[164:167], off offset:256
	v_cndmask_b32_e32 v153, v221, v153, vcc
	v_lshlrev_b32_e32 v153, 2, v153
	ds_bpermute_b32 v153, v153, v152
	s_and_saveexec_b64 s[22:23], s[40:41]
	s_cbranch_execz .LBB0_1353
	v_lshl_add_u64 v[154:155], v[2:3], 2, s[20:21]
	s_waitcnt lgkmcnt(0)
	v_add_f32_e32 v152, v152, v153
	global_atomic_add_f32 v[154:155], v152, off

;     __device__ __forceinline__ void mid(f32x4 (&acc)[2][2][4][2], const Unit& u, int wr, int wc, int fr, int fq) const {
;         if (!sab) return;
;         const int row0 = u.pm * BM + wr * 64 + fr;
;         float2 sv[2][4];
; #pragma unroll
;         for (int ai = 0; ai < 2; ++ai)
; #pragma unroll
;             for (int m = 0; m < 4; ++m) sv[ai][m] = *(const float2*)(sab + 2 * (size_t)(row0 + ai * HALF + m * 16));
; #pragma unroll
;         for (int ai = 0; ai < 2; ++ai)
; #pragma unroll
;             for (int m = 0; m < 4; ++m) { const float ratio = sqrtf((sv[ai][m].y * (1.f / GW) + EPS) / (sv[ai][m].x * (1.f / GW) + EPS));
; #pragma unroll
;                 for (int bj = 0; bj < 2; ++bj)
; #pragma unroll
;                     for (int n = 0; n < 2; ++n) acc[ai][bj][m][n] = acc[ai][bj][m][n] * ratio; }
;     }
.LBB0_1386:
	s_andn2_b64 vcc, exec, s[22:23]
	s_cbranch_vccnz .LBB0_1389
	s_andn2_b64 vcc, exec, s[58:59]
	s_cbranch_vccnz .LBB0_1389
	v_lshl_add_u32 v2, s88, 8, v191
	v_ashrrev_i32_e32 v3, 31, v2
	s_waitcnt lgkmcnt(0)
	v_lshl_add_u64 v[132:133], v[2:3], 3, s[48:49]
	flat_load_dwordx2 v[140:141], v[132:133]
	v_or_b32_e32 v134, 16, v2
	v_ashrrev_i32_e32 v135, 31, v134
	v_lshl_add_u64 v[138:139], v[134:135], 3, s[48:49]
	flat_load_dwordx2 v[138:139], v[138:139]
	v_or_b32_e32 v134, 32, v2
	v_ashrrev_i32_e32 v135, 31, v134
	v_lshl_add_u64 v[136:137], v[134:135], 3, s[48:49]
	flat_load_dwordx2 v[136:137], v[136:137]
	v_or_b32_e32 v2, 48, v2
	v_ashrrev_i32_e32 v3, 31, v2
	s_mov_b32 s2, 0x358637bd
	v_lshl_add_u64 v[134:135], v[2:3], 3, s[48:49]
	v_mov_b64_e32 v[2:3], s[2:3]
	s_mov_b32 s38, 0x3a800000
	flat_load_dwordx2 v[134:135], v[134:135]
	flat_load_dwordx2 v[160:161], v[132:133] offset:1024
	flat_load_dwordx2 v[162:163], v[132:133] offset:1152
	flat_load_dwordx2 v[164:165], v[132:133] offset:1280
	flat_load_dwordx2 v[166:167], v[132:133] offset:1408
	s_mov_b32 s22, 0xf800000
	s_waitcnt vmcnt(0) lgkmcnt(0)
	v_pk_fma_f32 v[140:141], v[140:141], s[38:39], v[2:3] op_sel_hi:[1,0,0]
	s_nop 0
	v_div_scale_f32 v0, s[2:3], v140, v140, v141
	v_rcp_f32_e32 v142, v0
	v_pk_fma_f32 v[138:139], v[138:139], s[38:39], v[2:3] op_sel_hi:[1,0,0]
	v_fma_f32 v143, -v0, v142, 1.0
	v_fmac_f32_e32 v142, v143, v142
	v_div_scale_f32 v143, vcc, v141, v140, v141
	v_mul_f32_e32 v144, v143, v142
	v_fma_f32 v145, -v0, v144, v143
	v_fmac_f32_e32 v144, v145, v142
	v_fma_f32 v0, -v0, v144, v143
	v_div_fmas_f32 v0, v0, v142, v144
	v_div_fixup_f32 v0, v0, v140, v141
	v_cmp_gt_f32_e32 vcc, s22, v0
	v_mul_f32_e32 v140, 0x4f800000, v0
	v_pk_fma_f32 v[136:137], v[136:137], s[38:39], v[2:3] op_sel_hi:[1,0,0]
	v_cndmask_b32_e32 v0, v0, v140, vcc
	v_sqrt_f32_e32 v140, v0
	v_pk_fma_f32 v[134:135], v[134:135], s[38:39], v[2:3] op_sel_hi:[1,0,0]
	v_add_u32_e32 v141, -1, v140
	v_fma_f32 v142, -v141, v140, v0
	v_cmp_ge_f32_e64 s[44:45], 0, v142
	v_add_u32_e32 v142, 1, v140
	s_nop 0
	v_cndmask_b32_e64 v141, v140, v141, s[44:45]
	v_fma_f32 v140, -v142, v140, v0
	v_cmp_lt_f32_e64 s[44:45], 0, v140
	s_nop 1
	v_cndmask_b32_e64 v140, v141, v142, s[44:45]
	v_mul_f32_e32 v141, 0x37800000, v140
	v_cndmask_b32_e32 v140, v140, v141, vcc
	v_cmp_class_f32_e32 vcc, v0, v228
	s_nop 1
	v_cndmask_b32_e32 v0, v140, v0, vcc
	v_pk_mul_f32 v[130:131], v[130:131], v[0:1] op_sel_hi:[1,0]
	v_pk_mul_f32 v[128:129], v[128:129], v[0:1] op_sel_hi:[1,0]
	v_pk_mul_f32 v[126:127], v[126:127], v[0:1] op_sel_hi:[1,0]
	v_pk_mul_f32 v[124:125], v[124:125], v[0:1] op_sel_hi:[1,0]
	v_pk_mul_f32 v[98:99], v[98:99], v[0:1] op_sel_hi:[1,0]
	v_pk_mul_f32 v[96:97], v[96:97], v[0:1] op_sel_hi:[1,0]
	v_pk_mul_f32 v[94:95], v[94:95], v[0:1] op_sel_hi:[1,0]
	v_pk_mul_f32 v[92:93], v[92:93], v[0:1] op_sel_hi:[1,0]
	v_div_scale_f32 v0, s[2:3], v138, v138, v139
	v_rcp_f32_e32 v140, v0
	s_nop 0
	v_fma_f32 v141, -v0, v140, 1.0
	v_fmac_f32_e32 v140, v141, v140
	v_div_scale_f32 v141, vcc, v139, v138, v139
	v_mul_f32_e32 v142, v141, v140
	v_fma_f32 v143, -v0, v142, v141
	v_fmac_f32_e32 v142, v143, v140
	v_fma_f32 v0, -v0, v142, v141
	v_div_fmas_f32 v0, v0, v140, v142
	v_div_fixup_f32 v0, v0, v138, v139
	v_cmp_gt_f32_e32 vcc, s22, v0
	v_mul_f32_e32 v138, 0x4f800000, v0
	s_nop 0
	v_cndmask_b32_e32 v0, v0, v138, vcc
	v_sqrt_f32_e32 v138, v0
	s_nop 0
	v_add_u32_e32 v139, -1, v138
	v_fma_f32 v140, -v139, v138, v0
	v_cmp_ge_f32_e64 s[44:45], 0, v140
	v_add_u32_e32 v140, 1, v138
	s_nop 0
	v_cndmask_b32_e64 v139, v138, v139, s[44:45]
	v_fma_f32 v138, -v140, v138, v0
	v_cmp_lt_f32_e64 s[44:45], 0, v138
	s_nop 1
	v_cndmask_b32_e64 v138, v139, v140, s[44:45]
	v_mul_f32_e32 v139, 0x37800000, v138
	v_cndmask_b32_e32 v138, v138, v139, vcc
	v_cmp_class_f32_e32 vcc, v0, v228
	s_nop 1
	v_cndmask_b32_e32 v0, v138, v0, vcc
	v_pk_mul_f32 v[122:123], v[122:123], v[0:1] op_sel_hi:[1,0]
	v_pk_mul_f32 v[120:121], v[120:121], v[0:1] op_sel_hi:[1,0]
	v_pk_mul_f32 v[118:119], v[118:119], v[0:1] op_sel_hi:[1,0]
	v_pk_mul_f32 v[116:117], v[116:117], v[0:1] op_sel_hi:[1,0]
	v_pk_mul_f32 v[90:91], v[90:91], v[0:1] op_sel_hi:[1,0]
	v_pk_mul_f32 v[88:89], v[88:89], v[0:1] op_sel_hi:[1,0]
	v_pk_mul_f32 v[86:87], v[86:87], v[0:1] op_sel_hi:[1,0]
	v_pk_mul_f32 v[84:85], v[84:85], v[0:1] op_sel_hi:[1,0]
	v_div_scale_f32 v0, s[2:3], v136, v136, v137
	v_rcp_f32_e32 v138, v0
	s_nop 0
	v_fma_f32 v139, -v0, v138, 1.0
	v_fmac_f32_e32 v138, v139, v138
	v_div_scale_f32 v139, vcc, v137, v136, v137
	v_mul_f32_e32 v140, v139, v138
	v_fma_f32 v141, -v0, v140, v139
	v_fmac_f32_e32 v140, v141, v138
	v_fma_f32 v0, -v0, v140, v139
	v_div_fmas_f32 v0, v0, v138, v140
	v_div_fixup_f32 v0, v0, v136, v137
	v_cmp_gt_f32_e32 vcc, s22, v0
	v_mul_f32_e32 v136, 0x4f800000, v0
	s_nop 0
	v_cndmask_b32_e32 v0, v0, v136, vcc
	v_sqrt_f32_e32 v136, v0
	s_nop 0
	v_add_u32_e32 v137, -1, v136
	v_fma_f32 v138, -v137, v136, v0
	v_cmp_ge_f32_e64 s[44:45], 0, v138
	v_add_u32_e32 v138, 1, v136
	s_nop 0
	v_cndmask_b32_e64 v137, v136, v137, s[44:45]
	v_fma_f32 v136, -v138, v136, v0
	v_cmp_lt_f32_e64 s[44:45], 0, v136
	s_nop 1
	v_cndmask_b32_e64 v136, v137, v138, s[44:45]
	v_mul_f32_e32 v137, 0x37800000, v136
	v_cndmask_b32_e32 v136, v136, v137, vcc
	v_cmp_class_f32_e32 vcc, v0, v228
	s_nop 1
	v_cndmask_b32_e32 v0, v136, v0, vcc
	v_pk_mul_f32 v[114:115], v[114:115], v[0:1] op_sel_hi:[1,0]
	v_pk_mul_f32 v[112:113], v[112:113], v[0:1] op_sel_hi:[1,0]
	v_pk_mul_f32 v[110:111], v[110:111], v[0:1] op_sel_hi:[1,0]
	v_pk_mul_f32 v[108:109], v[108:109], v[0:1] op_sel_hi:[1,0]
	v_pk_mul_f32 v[82:83], v[82:83], v[0:1] op_sel_hi:[1,0]
;     __device__ __forceinline__ void mid(f32x4 (&acc)[2][2][4][2], const Unit& u, int wr, int wc, int fr, int fq) const {
;     ...
;         for (int ai = 0; ai < 2; ++ai)
; #pragma unroll
;             for (int m = 0; m < 4; ++m) { const float ratio = sqrtf((sv[ai][m].y * (1.f / GW) + EPS) / (sv[ai][m].x * (1.f / GW) + EPS));
; #pragma unroll
;                 for (int bj = 0; bj < 2; ++bj)
; #pragma unroll
;                     for (int n = 0; n < 2; ++n) acc[ai][bj][m][n] = acc[ai][bj][m][n] * ratio; }
	v_pk_mul_f32 v[80:81], v[80:81], v[0:1] op_sel_hi:[1,0]
	v_pk_mul_f32 v[78:79], v[78:79], v[0:1] op_sel_hi:[1,0]
	v_pk_mul_f32 v[76:77], v[76:77], v[0:1] op_sel_hi:[1,0]
	v_div_scale_f32 v0, s[2:3], v134, v134, v135
	v_rcp_f32_e32 v136, v0
	s_nop 0
	v_fma_f32 v137, -v0, v136, 1.0
	v_fmac_f32_e32 v136, v137, v136
	v_div_scale_f32 v137, vcc, v135, v134, v135
	v_mul_f32_e32 v138, v137, v136
	v_fma_f32 v139, -v0, v138, v137
	v_fmac_f32_e32 v138, v139, v136
	v_fma_f32 v0, -v0, v138, v137
	v_div_fmas_f32 v0, v0, v136, v138
	v_div_fixup_f32 v0, v0, v134, v135
	v_cmp_gt_f32_e32 vcc, s22, v0
	v_mul_f32_e32 v134, 0x4f800000, v0
	s_nop 0
	v_cndmask_b32_e32 v0, v0, v134, vcc
	v_sqrt_f32_e32 v134, v0
	s_nop 0
	v_add_u32_e32 v135, -1, v134
	v_fma_f32 v136, -v135, v134, v0
	v_cmp_ge_f32_e64 s[44:45], 0, v136
	v_add_u32_e32 v136, 1, v134
	s_nop 0
	v_cndmask_b32_e64 v135, v134, v135, s[44:45]
	v_fma_f32 v134, -v136, v134, v0
	v_cmp_lt_f32_e64 s[44:45], 0, v134
	s_nop 1
	v_cndmask_b32_e64 v134, v135, v136, s[44:45]
	v_mul_f32_e32 v135, 0x37800000, v134
	v_cndmask_b32_e32 v134, v134, v135, vcc
	v_cmp_class_f32_e32 vcc, v0, v228
	s_nop 1
	v_cndmask_b32_e32 v0, v134, v0, vcc
	v_mov_b64_e32 v[134:135], v[160:161]
	v_pk_mul_f32 v[106:107], v[106:107], v[0:1] op_sel_hi:[1,0]
	v_pk_mul_f32 v[104:105], v[104:105], v[0:1] op_sel_hi:[1,0]
	v_pk_mul_f32 v[102:103], v[102:103], v[0:1] op_sel_hi:[1,0]
	v_pk_mul_f32 v[100:101], v[100:101], v[0:1] op_sel_hi:[1,0]
	v_pk_mul_f32 v[74:75], v[74:75], v[0:1] op_sel_hi:[1,0]
	v_pk_mul_f32 v[72:73], v[72:73], v[0:1] op_sel_hi:[1,0]
	v_pk_mul_f32 v[70:71], v[70:71], v[0:1] op_sel_hi:[1,0]
	v_pk_mul_f32 v[68:69], v[68:69], v[0:1] op_sel_hi:[1,0]
	s_waitcnt vmcnt(0) lgkmcnt(0)
	v_pk_fma_f32 v[134:135], v[134:135], s[38:39], v[2:3] op_sel_hi:[1,0,0]
	s_nop 0
	v_div_scale_f32 v0, s[2:3], v134, v134, v135
	v_rcp_f32_e32 v136, v0
	s_nop 0
	v_fma_f32 v137, -v0, v136, 1.0
	v_fmac_f32_e32 v136, v137, v136
	v_div_scale_f32 v137, vcc, v135, v134, v135
	v_mul_f32_e32 v138, v137, v136
	v_fma_f32 v139, -v0, v138, v137
	v_fmac_f32_e32 v138, v139, v136
	v_fma_f32 v0, -v0, v138, v137
	v_div_fmas_f32 v0, v0, v136, v138
	v_div_fixup_f32 v0, v0, v134, v135
	v_cmp_gt_f32_e32 vcc, s22, v0
	v_mul_f32_e32 v134, 0x4f800000, v0
	s_nop 0
	v_cndmask_b32_e32 v0, v0, v134, vcc
	v_sqrt_f32_e32 v134, v0
	s_nop 0
	v_add_u32_e32 v135, -1, v134
	v_fma_f32 v136, -v135, v134, v0
	v_cmp_ge_f32_e64 s[44:45], 0, v136
	v_add_u32_e32 v136, 1, v134
	s_nop 0
	v_cndmask_b32_e64 v135, v134, v135, s[44:45]
	v_fma_f32 v134, -v136, v134, v0
	v_cmp_lt_f32_e64 s[44:45], 0, v134
	s_nop 1
	v_cndmask_b32_e64 v134, v135, v136, s[44:45]
	v_mul_f32_e32 v135, 0x37800000, v134
	v_cndmask_b32_e32 v134, v134, v135, vcc
	v_cmp_class_f32_e32 vcc, v0, v228
	s_nop 1
	v_cndmask_b32_e32 v0, v134, v0, vcc
	v_mov_b64_e32 v[134:135], v[162:163]
	v_pk_mul_f32 v[66:67], v[66:67], v[0:1] op_sel_hi:[1,0]
	v_pk_mul_f32 v[64:65], v[64:65], v[0:1] op_sel_hi:[1,0]
	v_pk_mul_f32 v[62:63], v[62:63], v[0:1] op_sel_hi:[1,0]
	v_pk_mul_f32 v[60:61], v[60:61], v[0:1] op_sel_hi:[1,0]
	v_pk_mul_f32 v[34:35], v[34:35], v[0:1] op_sel_hi:[1,0]
	v_pk_mul_f32 v[32:33], v[32:33], v[0:1] op_sel_hi:[1,0]
	v_pk_mul_f32 v[30:31], v[30:31], v[0:1] op_sel_hi:[1,0]
	v_pk_mul_f32 v[28:29], v[28:29], v[0:1] op_sel_hi:[1,0]
	s_waitcnt vmcnt(0) lgkmcnt(0)
;     __device__ __forceinline__ void mid(f32x4 (&acc)[2][2][4][2], const Unit& u, int wr, int wc, int fr, int fq) const {
;     ...
;         for (int ai = 0; ai < 2; ++ai)
; #pragma unroll
;             for (int m = 0; m < 4; ++m) { const float ratio = sqrtf((sv[ai][m].y * (1.f / GW) + EPS) / (sv[ai][m].x * (1.f / GW) + EPS));
; #pragma unroll
;                 for (int bj = 0; bj < 2; ++bj)
; #pragma unroll
;                     for (int n = 0; n < 2; ++n) acc[ai][bj][m][n] = acc[ai][bj][m][n] * ratio; }
	v_pk_fma_f32 v[134:135], v[134:135], s[38:39], v[2:3] op_sel_hi:[1,0,0]
	s_nop 0
	v_div_scale_f32 v0, s[2:3], v134, v134, v135
	v_rcp_f32_e32 v136, v0
	s_nop 0
	v_fma_f32 v137, -v0, v136, 1.0
	v_fmac_f32_e32 v136, v137, v136
	v_div_scale_f32 v137, vcc, v135, v134, v135
	v_mul_f32_e32 v138, v137, v136
	v_fma_f32 v139, -v0, v138, v137
	v_fmac_f32_e32 v138, v139, v136
	v_fma_f32 v0, -v0, v138, v137
	v_div_fmas_f32 v0, v0, v136, v138
	v_div_fixup_f32 v0, v0, v134, v135
	v_cmp_gt_f32_e32 vcc, s22, v0
	v_mul_f32_e32 v134, 0x4f800000, v0
	s_nop 0
	v_cndmask_b32_e32 v0, v0, v134, vcc
	v_sqrt_f32_e32 v134, v0
	s_nop 0
	v_add_u32_e32 v135, -1, v134
	v_fma_f32 v136, -v135, v134, v0
	v_cmp_ge_f32_e64 s[44:45], 0, v136
	v_add_u32_e32 v136, 1, v134
	s_nop 0
	v_cndmask_b32_e64 v135, v134, v135, s[44:45]
	v_fma_f32 v134, -v136, v134, v0
	v_cmp_lt_f32_e64 s[44:45], 0, v134
	s_nop 1
	v_cndmask_b32_e64 v134, v135, v136, s[44:45]
	v_mul_f32_e32 v135, 0x37800000, v134
	v_cndmask_b32_e32 v134, v134, v135, vcc
	v_cmp_class_f32_e32 vcc, v0, v228
	s_nop 1
	v_cndmask_b32_e32 v0, v134, v0, vcc
	v_mov_b64_e32 v[134:135], v[164:165]
	v_pk_mul_f32 v[58:59], v[58:59], v[0:1] op_sel_hi:[1,0]
	v_mov_b64_e32 v[132:133], v[166:167]
	v_pk_mul_f32 v[56:57], v[56:57], v[0:1] op_sel_hi:[1,0]
	v_pk_mul_f32 v[54:55], v[54:55], v[0:1] op_sel_hi:[1,0]
	v_pk_mul_f32 v[52:53], v[52:53], v[0:1] op_sel_hi:[1,0]
	v_pk_mul_f32 v[26:27], v[26:27], v[0:1] op_sel_hi:[1,0]
	v_pk_mul_f32 v[24:25], v[24:25], v[0:1] op_sel_hi:[1,0]
	v_pk_mul_f32 v[22:23], v[22:23], v[0:1] op_sel_hi:[1,0]
	v_pk_mul_f32 v[20:21], v[20:21], v[0:1] op_sel_hi:[1,0]
	s_waitcnt vmcnt(0) lgkmcnt(0)
	v_pk_fma_f32 v[134:135], v[134:135], s[38:39], v[2:3] op_sel_hi:[1,0,0]
	s_nop 0
	v_div_scale_f32 v0, s[2:3], v134, v134, v135
	v_rcp_f32_e32 v136, v0
	v_pk_fma_f32 v[2:3], v[132:133], s[38:39], v[2:3] op_sel_hi:[1,0,0]
	v_fma_f32 v137, -v0, v136, 1.0
	v_fmac_f32_e32 v136, v137, v136
	v_div_scale_f32 v137, vcc, v135, v134, v135
	v_mul_f32_e32 v138, v137, v136
	v_fma_f32 v139, -v0, v138, v137
	v_fmac_f32_e32 v138, v139, v136
	v_fma_f32 v0, -v0, v138, v137
	v_div_fmas_f32 v0, v0, v136, v138
	v_div_fixup_f32 v0, v0, v134, v135
	v_cmp_gt_f32_e32 vcc, s22, v0
	v_mul_f32_e32 v134, 0x4f800000, v0
	s_nop 0
	v_cndmask_b32_e32 v0, v0, v134, vcc
	v_sqrt_f32_e32 v134, v0
	s_nop 0
	v_add_u32_e32 v135, -1, v134
	v_fma_f32 v136, -v135, v134, v0
	v_cmp_ge_f32_e64 s[44:45], 0, v136
	v_add_u32_e32 v136, 1, v134
	s_nop 0
	v_cndmask_b32_e64 v135, v134, v135, s[44:45]
	v_fma_f32 v134, -v136, v134, v0
	v_cmp_lt_f32_e64 s[44:45], 0, v134
	s_nop 1
	v_cndmask_b32_e64 v134, v135, v136, s[44:45]
	v_mul_f32_e32 v135, 0x37800000, v134
	v_cndmask_b32_e32 v134, v134, v135, vcc
	v_cmp_class_f32_e32 vcc, v0, v228
	s_nop 1
	v_cndmask_b32_e32 v0, v134, v0, vcc
	v_pk_mul_f32 v[50:51], v[50:51], v[0:1] op_sel_hi:[1,0]
	v_pk_mul_f32 v[48:49], v[48:49], v[0:1] op_sel_hi:[1,0]
	v_pk_mul_f32 v[46:47], v[46:47], v[0:1] op_sel_hi:[1,0]
	v_pk_mul_f32 v[44:45], v[44:45], v[0:1] op_sel_hi:[1,0]
	v_pk_mul_f32 v[18:19], v[18:19], v[0:1] op_sel_hi:[1,0]
	v_pk_mul_f32 v[16:17], v[16:17], v[0:1] op_sel_hi:[1,0]
	v_pk_mul_f32 v[14:15], v[14:15], v[0:1] op_sel_hi:[1,0]
	v_pk_mul_f32 v[12:13], v[12:13], v[0:1] op_sel_hi:[1,0]
	v_div_scale_f32 v0, s[2:3], v2, v2, v3
	v_rcp_f32_e32 v132, v0
	s_nop 0
	v_fma_f32 v133, -v0, v132, 1.0
	v_fmac_f32_e32 v132, v133, v132
	v_div_scale_f32 v133, vcc, v3, v2, v3
	v_mul_f32_e32 v134, v133, v132
	v_fma_f32 v135, -v0, v134, v133
	v_fmac_f32_e32 v134, v135, v132
	v_fma_f32 v0, -v0, v134, v133
	v_div_fmas_f32 v0, v0, v132, v134
	v_div_fixup_f32 v0, v0, v2, v3
	v_cmp_gt_f32_e32 vcc, s22, v0
	v_mul_f32_e32 v2, 0x4f800000, v0
	s_nop 0
	v_cndmask_b32_e32 v0, v0, v2, vcc
	v_sqrt_f32_e32 v2, v0
	s_nop 0
	v_add_u32_e32 v3, -1, v2
	v_fma_f32 v132, -v3, v2, v0
	v_cmp_ge_f32_e64 s[44:45], 0, v132
	v_add_u32_e32 v132, 1, v2
	s_nop 0
	v_cndmask_b32_e64 v3, v2, v3, s[44:45]
	v_fma_f32 v2, -v132, v2, v0
	v_cmp_lt_f32_e64 s[44:45], 0, v2
	s_nop 1
	v_cndmask_b32_e64 v2, v3, v132, s[44:45]
	v_mul_f32_e32 v3, 0x37800000, v2
	v_cndmask_b32_e32 v2, v2, v3, vcc
	v_cmp_class_f32_e32 vcc, v0, v228
	s_nop 1
	v_cndmask_b32_e32 v0, v2, v0, vcc
	v_pk_mul_f32 v[42:43], v[42:43], v[0:1] op_sel_hi:[1,0]
	v_pk_mul_f32 v[40:41], v[40:41], v[0:1] op_sel_hi:[1,0]
	v_pk_mul_f32 v[38:39], v[38:39], v[0:1] op_sel_hi:[1,0]
	v_pk_mul_f32 v[36:37], v[36:37], v[0:1] op_sel_hi:[1,0]
	v_pk_mul_f32 v[10:11], v[10:11], v[0:1] op_sel_hi:[1,0]
	v_pk_mul_f32 v[8:9], v[8:9], v[0:1] op_sel_hi:[1,0]
	v_pk_mul_f32 v[6:7], v[6:7], v[0:1] op_sel_hi:[1,0]
	v_pk_mul_f32 v[4:5], v[4:5], v[0:1] op_sel_hi:[1,0]

; #define PG8_WAIT_V(n) asm volatile("s_waitcnt vmcnt(" #n ")" ::: "memory")
; #define PG8_BAR __builtin_amdgcn_s_barrier()
; template <class Epi, class Sched, bool ALIGN_EPI = false, bool SP2 = false>
; __device__ __forceinline__ void gemm_phase(PG8_LAS unsigned char* lds, const Gemm g, const Sched& S, const Epi& E) {
;     ...
;         const bool has_next = S.next(ui + 1, nxt);
;         const char* nA = has_next ? (const char*)g.A + (size_t)nxt.pm * tstep + (size_t)nxt.kt0 * kstep : cA; const char* nB = has_next ? (const char*)g.Bt + (size_t)nxt.pn * tstep + (size_t)nxt.kt0 * kstep : cB;
;         const int nt = cur.nkt;
;         for (int t = 0; t < nt; t += 2) {
;             const bool last = (t == nt - 2);
;             const char* a1 = cA + (size_t)(t + 1) * kstep;
;             const char* a2 = last ? nA : cA + (size_t)(t + 2) * kstep; const char* b2 = last ? nB : cB + (size_t)(t + 2) * kstep;
;             const char* a3 = a2 + kstep; const char* b3 = b2 + kstep;
;             if (last && has_next) S.a_ready(nxt);
;     ...
;     PG8_WAIT_V(0);
;     if constexpr (!ALIGN_EPI) { if (wr == 0) PG8_BAR; }
;     PG8_BAR;
.LBB0_1400:
	s_ashr_i32 s63, s62, 31
	s_lshl_b64 s[2:3], s[62:63], 20
	s_add_u32 s45, s12, s2
	s_addc_u32 s63, s13, s3
	s_ashr_i32 s77, s76, 31
	s_lshl_b64 s[2:3], s[76:77], 7
	s_add_u32 s78, s45, s2
	s_addc_u32 s79, s63, s3
	s_and_b64 vcc, exec, s[42:43]
	s_mov_b64 s[80:81], s[22:23]
	s_cbranch_vccz .LBB0_1332
	s_branch .LBB0_1333
.LBB0_1408:
	s_waitcnt vmcnt(0)
	v_readlane_b32 s60, v250, 5
	v_readlane_b32 s90, v249, 49
	v_readlane_b32 s61, v250, 6
	v_readlane_b32 s71, v250, 0
	s_mov_b64 s[56:57], s[94:95]
	v_readlane_b32 s91, v249, 50
	s_barrier

; __global__ void __launch_bounds__(NTHREADS, 2) mega(Args a) {
	.amdhsa_kernel _Z4mega4Args
		.amdhsa_group_segment_fixed_size 0
		.amdhsa_private_segment_fixed_size 0
		.amdhsa_kernarg_size 480
		.amdhsa_user_sgpr_count 2
		.amdhsa_user_sgpr_dispatch_ptr 0
		.amdhsa_user_sgpr_queue_ptr 0
		.amdhsa_user_sgpr_kernarg_segment_ptr 1
		.amdhsa_user_sgpr_dispatch_id 0
		.amdhsa_user_sgpr_kernarg_preload_length 0
		.amdhsa_user_sgpr_kernarg_preload_offset 0
		.amdhsa_user_sgpr_private_segment_size 0
		.amdhsa_uses_dynamic_stack 0
		.amdhsa_enable_private_segment 0
		.amdhsa_system_sgpr_workgroup_id_x 1
		.amdhsa_system_sgpr_workgroup_id_y 0
		.amdhsa_system_sgpr_workgroup_id_z 0
		.amdhsa_system_sgpr_workgroup_info 0
		.amdhsa_system_vgpr_workitem_id 2
		.amdhsa_next_free_vgpr 251
		.amdhsa_next_free_sgpr 102
		.amdhsa_accum_offset 252
		.amdhsa_reserve_vcc 1
		.amdhsa_float_round_mode_32 0
		.amdhsa_float_round_mode_16_64 0
		.amdhsa_float_denorm_mode_32 3
		.amdhsa_float_denorm_mode_16_64 3
		.amdhsa_dx10_clamp 1
		.amdhsa_ieee_mode 1
		.amdhsa_fp16_overflow 0
		.amdhsa_tg_split 0
		.amdhsa_exception_fp_ieee_invalid_op 0
		.amdhsa_exception_fp_denorm_src 0
		.amdhsa_exception_fp_ieee_div_zero 0
		.amdhsa_exception_fp_ieee_overflow 0
		.amdhsa_exception_fp_ieee_underflow 0
		.amdhsa_exception_fp_ieee_inexact 0
		.amdhsa_exception_int_div_zero 0
	.end_amdhsa_kernel

; __global__ void __launch_bounds__(NTHREADS, 2) mega(Args a) {
amdhsa.kernels:
  - .agpr_count:     0
    .args:
      - .offset:         0
        .size:           224
        .value_kind:     by_value
      - .offset:         224
        .size:           4
        .value_kind:     hidden_block_count_x
      - .offset:         228
        .size:           4
        .value_kind:     hidden_block_count_y
      - .offset:         232
        .size:           4
        .value_kind:     hidden_block_count_z
      - .offset:         236
        .size:           2
        .value_kind:     hidden_group_size_x
      - .offset:         238
        .size:           2
        .value_kind:     hidden_group_size_y
      - .offset:         240
        .size:           2
        .value_kind:     hidden_group_size_z
      - .offset:         242
        .size:           2
        .value_kind:     hidden_remainder_x
      - .offset:         244
        .size:           2
        .value_kind:     hidden_remainder_y
      - .offset:         246
        .size:           2
        .value_kind:     hidden_remainder_z
      - .offset:         264
        .size:           8
        .value_kind:     hidden_global_offset_x
      - .offset:         272
        .size:           8
        .value_kind:     hidden_global_offset_y
      - .offset:         280
        .size:           8
        .value_kind:     hidden_global_offset_z
      - .offset:         288
        .size:           2
        .value_kind:     hidden_grid_dims
      - .offset:         312
        .size:           8
        .value_kind:     hidden_multigrid_sync_arg
      - .offset:         344
        .size:           4
        .value_kind:     hidden_dynamic_lds_size
    .group_segment_fixed_size: 0
    .kernarg_segment_align: 8
    .kernarg_segment_size: 480
    .language:       OpenCL C
    .language_version:
      - 2
      - 0
    .max_flat_workgroup_size: 512
    .name:           _Z4mega4Args
    .private_segment_fixed_size: 0
    .sgpr_count:     108
    .sgpr_spill_count: 133
    .symbol:         _Z4mega4Args.kd
    .uniform_work_group_size: 1
    .uses_dynamic_stack: false
    .vgpr_count:     251
    .vgpr_spill_count: 0
    .wavefront_size: 64
